# forget-prompt attention: PV V-fragment tr-reads also pipelined through a 6-buffer ring
# baseline (speedup 1.0000x reference)
.LBB0_492:
	v_exp_f32_e32 v2, v114
	v_exp_f32_e32 v3, v115
	v_exp_f32_e32 v8, v118
	v_exp_f32_e32 v9, v119
	v_exp_f32_e32 v10, v120
	v_exp_f32_e32 v11, v121
	v_add_u32_e32 v12, s78, v239
	v_cvt_pk_bf16_f32 v6, v2, v3
	v_add3_u32 v2, v12, v240, v241
	v_exp_f32_e32 v5, v116
	v_exp_f32_e32 v7, v117
	v_cvt_pk_bf16_f32 v8, v8, v9
	v_cvt_pk_bf16_f32 v9, v10, v11
	ds_read_b64_tr_b16 v[182:183], v2 offset:22528
	ds_read_b64_tr_b16 v[184:185], v2 offset:23680
	ds_read_b64_tr_b16 v[186:187], v2 offset:22592
	ds_read_b64_tr_b16 v[188:189], v2 offset:23744
	ds_read_b64_tr_b16 v[190:191], v2 offset:24832
	ds_read_b64_tr_b16 v[192:193], v2 offset:25984
	ds_read_b64_tr_b16 v[222:223], v2 offset:24896
	ds_read_b64_tr_b16 v[224:225], v2 offset:26048
	ds_read_b64_tr_b16 v[228:229], v2 offset:27136
	ds_read_b64_tr_b16 v[230:231], v2 offset:28288
	ds_read_b64_tr_b16 v[10:11], v2 offset:27200
	ds_read_b64_tr_b16 v[12:13], v2 offset:28352
	v_cvt_pk_bf16_f32 v7, v5, v7
	v_exp_f32_e32 v14, v122
	v_exp_f32_e32 v15, v123
	s_waitcnt lgkmcnt(10)
	v_mfma_f32_32x32x16_bf16 v[34:49], v[182:185], v[6:9], v[34:49]
	ds_read_b64_tr_b16 v[182:183], v2 offset:29440
	ds_read_b64_tr_b16 v[184:185], v2 offset:30592
	v_exp_f32_e32 v16, v124
	v_exp_f32_e32 v17, v125
	v_exp_f32_e32 v114, v126
	v_exp_f32_e32 v115, v127
	v_exp_f32_e32 v116, v128
	v_exp_f32_e32 v117, v129
	s_waitcnt lgkmcnt(10)
	v_mfma_f32_32x32x16_bf16 v[18:33], v[186:189], v[6:9], v[18:33]
	ds_read_b64_tr_b16 v[186:187], v2 offset:29504
	ds_read_b64_tr_b16 v[188:189], v2 offset:30656
	v_exp_f32_e32 v82, v82
	v_exp_f32_e32 v83, v83
	v_exp_f32_e32 v84, v84
	v_exp_f32_e32 v85, v85
	v_exp_f32_e32 v86, v86
	v_exp_f32_e32 v87, v87
	v_mfma_f32_32x32x16_bf16 v[50:65], v[134:137], v[6:9], v[50:65]
	v_cvt_pk_bf16_f32 v6, v14, v15
	v_cvt_pk_bf16_f32 v7, v16, v17
	v_cvt_pk_bf16_f32 v8, v114, v115
	v_cvt_pk_bf16_f32 v9, v116, v117
	v_exp_f32_e32 v88, v88
	v_exp_f32_e32 v89, v89
	v_exp_f32_e32 v90, v90
	s_waitcnt lgkmcnt(10)
	v_mfma_f32_32x32x16_bf16 v[34:49], v[190:193], v[6:9], v[34:49]
	ds_read_b64_tr_b16 v[190:191], v2 offset:31744
	ds_read_b64_tr_b16 v[192:193], v2 offset:32896
	v_exp_f32_e32 v91, v91
	v_exp_f32_e32 v92, v92
	v_exp_f32_e32 v93, v93
	v_exp_f32_e32 v94, v94
	v_exp_f32_e32 v95, v95
	v_exp_f32_e32 v96, v96
	s_waitcnt lgkmcnt(10)
	v_mfma_f32_32x32x16_bf16 v[18:33], v[222:225], v[6:9], v[18:33]
	ds_read_b64_tr_b16 v[222:223], v2 offset:31808
	ds_read_b64_tr_b16 v[224:225], v2 offset:32960
	v_exp_f32_e32 v97, v97
	v_exp_f32_e32 v98, v98
	v_exp_f32_e32 v99, v99
	v_exp_f32_e32 v100, v100
	v_exp_f32_e32 v101, v101
	v_exp_f32_e32 v102, v102
	v_mfma_f32_32x32x16_bf16 v[50:65], v[134:137], v[6:9], v[50:65]
	v_cvt_pk_bf16_f32 v6, v82, v83
	v_cvt_pk_bf16_f32 v7, v84, v85
	v_cvt_pk_bf16_f32 v8, v86, v87
	v_cvt_pk_bf16_f32 v9, v88, v89
	v_exp_f32_e32 v103, v103
	v_exp_f32_e32 v104, v104
	v_exp_f32_e32 v105, v105
	s_waitcnt lgkmcnt(10)
	v_mfma_f32_32x32x16_bf16 v[34:49], v[228:231], v[6:9], v[34:49]
	ds_read_b64_tr_b16 v[228:229], v2 offset:34048
	ds_read_b64_tr_b16 v[230:231], v2 offset:35200
	v_exp_f32_e32 v106, v106
	v_exp_f32_e32 v107, v107
	v_exp_f32_e32 v108, v108
	v_exp_f32_e32 v109, v109
	v_exp_f32_e32 v110, v110
	v_exp_f32_e32 v111, v111
	s_waitcnt lgkmcnt(10)
	v_mfma_f32_32x32x16_bf16 v[18:33], v[10:13], v[6:9], v[18:33]
	ds_read_b64_tr_b16 v[10:11], v2 offset:34112
	ds_read_b64_tr_b16 v[12:13], v2 offset:35264
	v_exp_f32_e32 v112, v112
	v_exp_f32_e32 v113, v113
	v_exp_f32_e32 v66, v66
	v_exp_f32_e32 v67, v67
	v_exp_f32_e32 v68, v68
	v_exp_f32_e32 v69, v69
	v_mfma_f32_32x32x16_bf16 v[50:65], v[134:137], v[6:9], v[50:65]
	v_cvt_pk_bf16_f32 v6, v90, v91
	v_cvt_pk_bf16_f32 v7, v92, v93
	v_cvt_pk_bf16_f32 v8, v94, v95
	v_cvt_pk_bf16_f32 v9, v96, v97
	v_exp_f32_e32 v70, v70
	v_exp_f32_e32 v71, v71
	v_exp_f32_e32 v72, v72
	s_waitcnt lgkmcnt(10)
	v_mfma_f32_32x32x16_bf16 v[34:49], v[182:185], v[6:9], v[34:49]
	ds_read_b64_tr_b16 v[182:183], v2 offset:36352
	ds_read_b64_tr_b16 v[184:185], v2 offset:37504
	v_exp_f32_e32 v73, v73
	v_exp_f32_e32 v74, v74
	v_exp_f32_e32 v75, v75
	v_exp_f32_e32 v76, v76
	v_exp_f32_e32 v77, v77
	v_exp_f32_e32 v78, v78
	s_waitcnt lgkmcnt(10)
	v_mfma_f32_32x32x16_bf16 v[18:33], v[186:189], v[6:9], v[18:33]
	ds_read_b64_tr_b16 v[186:187], v2 offset:36416
	ds_read_b64_tr_b16 v[188:189], v2 offset:37568
	v_exp_f32_e32 v79, v79
	v_exp_f32_e32 v80, v80
	v_exp_f32_e32 v81, v81
	s_mov_b64 s[72:73], 0
	v_mfma_f32_32x32x16_bf16 v[50:65], v[134:137], v[6:9], v[50:65]
	v_cvt_pk_bf16_f32 v6, v98, v99
	v_cvt_pk_bf16_f32 v7, v100, v101
	v_cvt_pk_bf16_f32 v8, v102, v103
	v_cvt_pk_bf16_f32 v9, v104, v105
	s_waitcnt lgkmcnt(10)
	s_nop 0
	v_mfma_f32_32x32x16_bf16 v[34:49], v[190:193], v[6:9], v[34:49]
	ds_read_b64_tr_b16 v[190:191], v2 offset:38656
	ds_read_b64_tr_b16 v[192:193], v2 offset:39808
	s_waitcnt lgkmcnt(10)
	v_mfma_f32_32x32x16_bf16 v[18:33], v[222:225], v[6:9], v[18:33]
	ds_read_b64_tr_b16 v[222:223], v2 offset:38720
	ds_read_b64_tr_b16 v[224:225], v2 offset:39872
	v_mfma_f32_32x32x16_bf16 v[50:65], v[134:137], v[6:9], v[50:65]
	v_cvt_pk_bf16_f32 v6, v106, v107
	v_cvt_pk_bf16_f32 v7, v108, v109
	v_cvt_pk_bf16_f32 v8, v110, v111
	v_cvt_pk_bf16_f32 v9, v112, v113
	s_waitcnt lgkmcnt(10)
	s_nop 0
	v_mfma_f32_32x32x16_bf16 v[34:49], v[228:231], v[6:9], v[34:49]
	s_waitcnt lgkmcnt(8)
	v_mfma_f32_32x32x16_bf16 v[18:33], v[10:13], v[6:9], v[18:33]
	v_mfma_f32_32x32x16_bf16 v[50:65], v[134:137], v[6:9], v[50:65]
	v_cvt_pk_bf16_f32 v6, v66, v67
	v_cvt_pk_bf16_f32 v7, v68, v69
	v_cvt_pk_bf16_f32 v8, v70, v71
	v_cvt_pk_bf16_f32 v9, v72, v73
	s_waitcnt lgkmcnt(6)
	s_nop 0
	v_mfma_f32_32x32x16_bf16 v[34:49], v[182:185], v[6:9], v[34:49]
	s_waitcnt lgkmcnt(4)
	v_mfma_f32_32x32x16_bf16 v[18:33], v[186:189], v[6:9], v[18:33]
	v_mfma_f32_32x32x16_bf16 v[50:65], v[134:137], v[6:9], v[50:65]
	v_cvt_pk_bf16_f32 v6, v74, v75
	v_cvt_pk_bf16_f32 v7, v76, v77
	v_cvt_pk_bf16_f32 v8, v78, v79
	v_cvt_pk_bf16_f32 v9, v80, v81
	s_waitcnt lgkmcnt(2)
	s_nop 0
	v_mfma_f32_32x32x16_bf16 v[34:49], v[190:193], v[6:9], v[34:49]
	s_waitcnt lgkmcnt(0)
	v_mfma_f32_32x32x16_bf16 v[18:33], v[222:225], v[6:9], v[18:33]
	v_mfma_f32_32x32x16_bf16 v[50:65], v[134:137], v[6:9], v[50:65]
